# ACT stores: plain write-through (sc1) instead of nt sc1
# speedup vs baseline: 1.0054x; 1.0054x over previous
.LBB0_86:
	s_add_i32 s3, s6, s42
	s_cmpk_gt_i32 s3, 0x3fff
	s_cselect_b64 s[10:11], -1, 0
	s_ashr_i32 s7, s6, 31
	s_lshl_b64 s[8:9], s[6:7], 12
	v_lshl_add_u64 v[48:49], v[46:47], 0, s[8:9]
	global_load_dwordx4 v[64:67], v[48:49], off
	global_load_dwordx4 v[38:41], v[48:49], off offset:1024
	global_load_dwordx4 v[22:25], v[48:49], off offset:3072
	global_load_dwordx4 v[30:33], v[48:49], off offset:2048
	s_cmpk_lt_i32 s3, 0x4000
	s_cselect_b32 s6, s3, s6
	s_ashr_i32 s7, s6, 31
	s_lshl_b64 s[6:7], s[6:7], 12
	v_lshl_add_u64 v[50:51], v[46:47], 0, s[6:7]
	global_load_dwordx4 v[42:45], v[50:51], off
	global_load_dwordx4 v[34:37], v[50:51], off offset:1024
	global_load_dwordx4 v[18:21], v[50:51], off offset:3072
	global_load_dwordx4 v[26:29], v[50:51], off offset:2048
	s_mov_b32 s6, 0x3a800000
	s_and_b64 s[8:9], exec, s[10:11]
	s_mov_b64 s[12:13], -1
	s_waitcnt vmcnt(7)
	v_pk_mul_f32 v[52:53], v[66:67], v[66:67]
	v_pk_mul_f32 v[54:55], v[64:65], v[64:65]
	s_waitcnt vmcnt(6)
	v_pk_mul_f32 v[56:57], v[40:41], v[40:41]
	v_pk_mul_f32 v[68:69], v[38:39], v[38:39]
	s_waitcnt vmcnt(4)
	v_mul_f32_e32 v0, v31, v31
	v_mul_f32_e32 v70, v33, v33
	v_mul_f32_e32 v74, v24, v24
	v_mul_f32_e32 v75, v25, v25
	v_pk_mov_b32 v[72:73], v[54:55], v[52:53] op_sel:[1,0]
	v_mov_b32_e32 v55, v53
	v_pk_mov_b32 v[52:53], v[68:69], v[56:57] op_sel:[1,0]
	v_mov_b32_e32 v69, v57
	v_pk_fma_f32 v[56:57], v[30:31], v[30:31], v[0:1] op_sel_hi:[1,1,0]
	v_pk_fma_f32 v[70:71], v[32:33], v[32:33], v[70:71] op_sel_hi:[1,1,0]
	v_pk_add_f32 v[54:55], v[72:73], v[54:55]
	v_pk_add_f32 v[52:53], v[52:53], v[68:69]
	v_mov_b32_e32 v57, v74
	v_mov_b32_e32 v71, v75
	v_mul_f32_e32 v76, v22, v22
	v_mul_f32_e32 v77, v23, v23
	v_pk_add_f32 v[54:55], v[54:55], v[54:55] op_sel:[0,1] op_sel_hi:[1,0]
	v_pk_add_f32 v[52:53], v[52:53], v[52:53] op_sel:[0,1] op_sel_hi:[1,0]
	v_pk_add_f32 v[56:57], v[56:57], v[70:71]
	s_waitcnt vmcnt(3)
	v_pk_mul_f32 v[68:69], v[44:45], v[44:45]
	v_pk_mul_f32 v[70:71], v[42:43], v[42:43]
	s_waitcnt vmcnt(2)
	v_pk_mul_f32 v[72:73], v[36:37], v[36:37]
	v_pk_mul_f32 v[74:75], v[34:35], v[34:35]
	v_mov_b32_e32 v55, v76
	v_mov_b32_e32 v53, v77
	v_pk_mov_b32 v[78:79], v[70:71], v[68:69] op_sel:[1,0]
	v_mov_b32_e32 v71, v69
	v_pk_mov_b32 v[68:69], v[74:75], v[72:73] op_sel:[1,0]
	v_mov_b32_e32 v75, v73
	s_waitcnt vmcnt(1)
	v_mul_f32_e32 v77, v18, v18
	s_waitcnt vmcnt(0)
	v_mul_f32_e32 v0, v27, v27
	v_mul_f32_e32 v76, v29, v29
	v_pk_add_f32 v[52:53], v[54:55], v[52:53]
	v_pk_add_f32 v[70:71], v[78:79], v[70:71]
	v_pk_add_f32 v[68:69], v[68:69], v[74:75]
	v_mul_f32_e32 v80, v19, v19
	v_mul_f32_e32 v81, v20, v20
	v_mul_f32_e32 v82, v21, v21
	v_pk_fma_f32 v[54:55], v[26:27], v[26:27], v[0:1] op_sel_hi:[1,1,0]
	v_pk_fma_f32 v[72:73], v[28:29], v[28:29], v[76:77] op_sel_hi:[1,1,0]
	v_pk_add_f32 v[52:53], v[52:53], v[56:57]
	v_pk_add_f32 v[56:57], v[70:71], v[70:71] op_sel:[0,1] op_sel_hi:[1,0]
	v_pk_add_f32 v[68:69], v[68:69], v[68:69] op_sel:[0,1] op_sel_hi:[1,0]
	v_mov_b32_e32 v55, v81
	v_mov_b32_e32 v73, v82
	v_mov_b32_e32 v57, v77
	v_mov_b32_e32 v69, v80
	v_pk_add_f32 v[54:55], v[54:55], v[72:73]
	v_pk_add_f32 v[56:57], v[56:57], v[68:69]
	v_mov_b32_e32 v71, v52
	v_pk_add_f32 v[54:55], v[56:57], v[54:55]
	s_nop 0
	v_mov_b32_e32 v70, v54
	v_mov_b32_e32 v52, v55
	v_pk_add_f32 v[52:53], v[70:71], v[52:53]
	ds_bpermute_b32 v55, v58, v53
	ds_bpermute_b32 v54, v58, v52
	s_waitcnt lgkmcnt(0)
	v_pk_add_f32 v[52:53], v[52:53], v[54:55]
	ds_bpermute_b32 v55, v59, v53
	ds_bpermute_b32 v54, v59, v52
	s_waitcnt lgkmcnt(0)
	v_pk_add_f32 v[52:53], v[52:53], v[54:55]
	ds_bpermute_b32 v55, v60, v53
	ds_bpermute_b32 v54, v60, v52
	s_waitcnt lgkmcnt(0)
	v_pk_add_f32 v[52:53], v[52:53], v[54:55]
	ds_bpermute_b32 v55, v61, v53
	ds_bpermute_b32 v54, v61, v52
	s_waitcnt lgkmcnt(0)
	v_pk_add_f32 v[52:53], v[52:53], v[54:55]
	ds_bpermute_b32 v55, v62, v53
	ds_bpermute_b32 v54, v62, v52
	s_waitcnt lgkmcnt(0)
	v_pk_add_f32 v[52:53], v[52:53], v[54:55]
	ds_bpermute_b32 v55, v63, v53
	ds_bpermute_b32 v54, v63, v52
	s_waitcnt lgkmcnt(0)
	v_pk_add_f32 v[52:53], v[52:53], v[54:55]
	s_nop 0
	v_pk_fma_f32 v[56:57], v[52:53], s[6:7], v[190:191] op_sel_hi:[1,0,0]
	s_nop 0
	v_mul_f32_e32 v0, 0x4b800000, v57
	v_cmp_gt_f32_e32 vcc, s96, v57
	v_cmp_gt_f32_e64 s[6:7], s96, v56
	s_nop 0
	v_cndmask_b32_e32 v0, v57, v0, vcc
	v_rsq_f32_e32 v0, v0
	s_nop 0
	v_mul_f32_e32 v52, 0x45800000, v0
	v_cndmask_b32_e32 v52, v0, v52, vcc
	v_mov_b32_e32 v53, v52
	v_pk_mul_f32 v[64:65], v[64:65], v[52:53] op_sel_hi:[1,0]
	v_pk_mul_f32 v[66:67], v[66:67], v[52:53] op_sel_hi:[1,0]
	v_pk_mul_f32 v[54:55], v[38:39], v[52:53]
	v_pk_mul_f32 v[66:67], v[4:5], v[66:67]
	v_pk_mul_f32 v[64:65], v[2:3], v[64:65]
	s_mov_b64 vcc, s[8:9]
	global_store_dwordx4 v[48:49], v[64:67], off sc1
	s_cbranch_vccz .LBB0_88
	v_mov_b32_e32 v38, v52
	v_mov_b32_e32 v39, v52
	v_pk_mul_f32 v[38:39], v[40:41], v[38:39]
	v_pk_mul_f32 v[64:65], v[6:7], v[54:55]
	v_pk_mul_f32 v[66:67], v[8:9], v[38:39]
	global_store_dwordx4 v[48:49], v[64:67], off offset:1024 sc1
	s_mov_b64 s[12:13], 0
.LBB0_88:
	v_mul_f32_e32 v0, 0x4b800000, v56
	v_cndmask_b32_e64 v0, v56, v0, s[6:7]
	v_rsq_f32_e32 v0, v0
	s_andn2_b64 vcc, exec, s[12:13]
	v_mul_f32_e32 v38, 0x45800000, v0
	v_cndmask_b32_e64 v38, v0, v38, s[6:7]
	v_mov_b32_e32 v39, v38
	s_cbranch_vccnz .LBB0_90
	v_mov_b32_e32 v56, v38
	v_mov_b32_e32 v57, v38
	v_pk_mul_f32 v[44:45], v[44:45], v[56:57]
	v_pk_mul_f32 v[42:43], v[42:43], v[38:39]
	v_pk_mul_f32 v[44:45], v[4:5], v[44:45]
	v_pk_mul_f32 v[42:43], v[2:3], v[42:43]
	global_store_dwordx4 v[50:51], v[42:45], off sc1
	v_pk_mul_f32 v[36:37], v[36:37], v[56:57]
	v_pk_mul_f32 v[34:35], v[34:35], v[38:39]
	v_mov_b32_e32 v42, v52
	v_mov_b32_e32 v43, v52
	v_pk_mul_f32 v[40:41], v[40:41], v[42:43]
	v_pk_mul_f32 v[36:37], v[8:9], v[36:37]
	v_pk_mul_f32 v[42:43], v[8:9], v[40:41]
	v_pk_mul_f32 v[40:41], v[6:7], v[54:55]
	v_pk_mul_f32 v[34:35], v[6:7], v[34:35]
	global_store_dwordx4 v[48:49], v[40:43], off offset:1024 sc1
	global_store_dwordx4 v[50:51], v[34:37], off offset:1024 sc1
.LBB0_90:
	s_nop 1
	v_mov_b32_e32 v34, v52
	v_mov_b32_e32 v35, v52
	v_pk_mul_f32 v[32:33], v[32:33], v[34:35]
	v_pk_mul_f32 v[30:31], v[30:31], v[52:53]
	v_pk_mul_f32 v[32:33], v[12:13], v[32:33]
	v_pk_mul_f32 v[30:31], v[10:11], v[30:31]
	s_mov_b64 s[6:7], -1
	s_and_b64 vcc, exec, s[10:11]
	v_pk_mul_f32 v[22:23], v[22:23], v[52:53]
	global_store_dwordx4 v[48:49], v[30:33], off offset:2048 sc1
	s_cbranch_vccnz .LBB0_92
	s_andn2_b64 vcc, exec, s[6:7]
	s_cbranch_vccnz .LBB0_85
	s_branch .LBB0_93
.LBB0_92:
	s_nop 0
	v_pk_mul_f32 v[30:31], v[24:25], v[34:35]
	s_nop 0
	v_pk_mul_f32 v[32:33], v[16:17], v[30:31]
	v_pk_mul_f32 v[30:31], v[14:15], v[22:23]
	global_store_dwordx4 v[48:49], v[30:33], off offset:3072 sc1
	s_cbranch_execnz .LBB0_85
.LBB0_93:
	s_nop 0
	v_mov_b32_e32 v30, v38
	v_mov_b32_e32 v31, v38
	v_mov_b32_e32 v53, v52
	v_pk_mul_f32 v[28:29], v[28:29], v[30:31]
	v_pk_mul_f32 v[26:27], v[26:27], v[38:39]
	v_pk_mul_f32 v[24:25], v[24:25], v[52:53]
	v_pk_mul_f32 v[20:21], v[20:21], v[30:31]
	v_pk_mul_f32 v[18:19], v[18:19], v[38:39]
	v_pk_mul_f32 v[28:29], v[12:13], v[28:29]
	v_pk_mul_f32 v[26:27], v[10:11], v[26:27]
	v_pk_mul_f32 v[24:25], v[16:17], v[24:25]
	v_pk_mul_f32 v[22:23], v[14:15], v[22:23]
	v_pk_mul_f32 v[20:21], v[16:17], v[20:21]
	v_pk_mul_f32 v[18:19], v[14:15], v[18:19]
	global_store_dwordx4 v[50:51], v[26:29], off offset:2048 sc1
	global_store_dwordx4 v[48:49], v[22:25], off offset:3072 sc1
	global_store_dwordx4 v[50:51], v[18:21], off offset:3072 sc1
	s_branch .LBB0_85

.Luc_fast0:
	v_pk_fma_f32 v[18:19], v[150:151], v[82:83], v[208:209]
	v_pk_fma_f32 v[26:27], v[158:159], v[90:91], v[216:217]
	v_pk_fma_f32 v[20:21], v[152:153], v[84:85], v[210:211]
	v_pk_fma_f32 v[28:29], v[160:161], v[92:93], v[218:219]
	v_pk_fma_f32 v[22:23], v[154:155], v[86:87], v[212:213]
	v_pk_fma_f32 v[30:31], v[162:163], v[94:95], v[220:221]
	v_pk_fma_f32 v[24:25], v[156:157], v[88:89], v[214:215]
	v_pk_fma_f32 v[32:33], v[164:165], v[96:97], v[222:223]
	v_pk_fma_f32 v[18:19], v[174:175], v[66:67], v[18:19]
	v_pk_fma_f32 v[26:27], v[142:143], v[74:75], v[26:27]
	v_pk_fma_f32 v[20:21], v[176:177], v[68:69], v[20:21]
	v_pk_fma_f32 v[28:29], v[144:145], v[76:77], v[28:29]
	v_pk_fma_f32 v[22:23], v[182:183], v[70:71], v[22:23]
	v_pk_fma_f32 v[30:31], v[146:147], v[78:79], v[30:31]
	v_pk_fma_f32 v[24:25], v[184:185], v[72:73], v[24:25]
	v_pk_fma_f32 v[32:33], v[148:149], v[80:81], v[32:33]
	v_pk_fma_f32 v[18:19], v[192:193], v[98:99], v[18:19]
	v_pk_fma_f32 v[26:27], v[200:201], v[106:107], v[26:27]
	v_pk_fma_f32 v[20:21], v[194:195], v[100:101], v[20:21]
	v_pk_fma_f32 v[28:29], v[202:203], v[108:109], v[28:29]
	v_pk_fma_f32 v[22:23], v[196:197], v[102:103], v[22:23]
	v_pk_fma_f32 v[30:31], v[204:205], v[110:111], v[30:31]
	v_pk_fma_f32 v[24:25], v[198:199], v[104:105], v[24:25]
	v_pk_fma_f32 v[32:33], v[206:207], v[112:113], v[32:33]
	v_pk_mul_f32 v[34:35], v[18:19], v[42:43] op_sel_hi:[1,0]
	v_pk_mul_f32 v[36:37], v[20:21], v[42:43] op_sel_hi:[1,0]
	v_pk_mul_f32 v[38:39], v[22:23], v[42:43] op_sel_hi:[1,0]
	v_pk_mul_f32 v[40:41], v[24:25], v[42:43] op_sel_hi:[1,0]
	v_exp_f32_e32 v34, v34
	v_exp_f32_e32 v35, v35
	v_exp_f32_e32 v36, v36
	v_exp_f32_e32 v37, v37
	v_exp_f32_e32 v38, v38
	v_exp_f32_e32 v39, v39
	v_exp_f32_e32 v40, v40
	v_exp_f32_e32 v41, v41
	v_pk_add_f32 v[34:35], v[34:35], 1.0 op_sel_hi:[1,0]
	v_pk_add_f32 v[36:37], v[36:37], 1.0 op_sel_hi:[1,0]
	v_pk_add_f32 v[38:39], v[38:39], 1.0 op_sel_hi:[1,0]
	v_pk_add_f32 v[40:41], v[40:41], 1.0 op_sel_hi:[1,0]
	v_rcp_f32_e32 v34, v34
	v_rcp_f32_e32 v35, v35
	v_rcp_f32_e32 v36, v36
	v_rcp_f32_e32 v37, v37
	v_rcp_f32_e32 v38, v38
	v_rcp_f32_e32 v39, v39
	v_rcp_f32_e32 v40, v40
	v_rcp_f32_e32 v41, v41
	v_pk_mul_f32 v[18:19], v[18:19], v[34:35]
	v_pk_mul_f32 v[20:21], v[20:21], v[36:37]
	v_pk_mul_f32 v[22:23], v[22:23], v[38:39]
	v_pk_mul_f32 v[24:25], v[24:25], v[40:41]
	v_pk_mul_f32 v[18:19], v[26:27], v[18:19]
	v_pk_mul_f32 v[20:21], v[28:29], v[20:21]
	v_pk_mul_f32 v[22:23], v[30:31], v[22:23]
	v_pk_mul_f32 v[24:25], v[32:33], v[24:25]
	v_cvt_pk_bf16_f32 v34, v18, v19
	v_cvt_pk_bf16_f32 v35, v20, v21
	v_cvt_pk_bf16_f32 v36, v22, v23
	v_cvt_pk_bf16_f32 v37, v24, v25
	global_store_dwordx4 v[50:51], v[34:37], off sc1
	s_and_b64 vcc, exec, s[78:79]
	s_cbranch_vccz .Luc_skip0
	v_mov_b64_e32 v[98:99], v[2:3]
	v_mov_b64_e32 v[100:101], v[4:5]
	v_mov_b64_e32 v[102:103], v[6:7]
	v_mov_b64_e32 v[104:105], v[8:9]
	v_mov_b64_e32 v[106:107], v[10:11]
	v_mov_b64_e32 v[108:109], v[12:13]
	v_mov_b64_e32 v[110:111], v[14:15]
	v_mov_b64_e32 v[112:113], v[16:17]

.Luc_fast1:
	v_pk_fma_f32 v[18:19], v[150:151], v[98:99], v[208:209]
	v_pk_fma_f32 v[26:27], v[158:159], v[106:107], v[216:217]
	v_pk_fma_f32 v[20:21], v[152:153], v[100:101], v[210:211]
	v_pk_fma_f32 v[28:29], v[160:161], v[108:109], v[218:219]
	v_pk_fma_f32 v[22:23], v[154:155], v[102:103], v[212:213]
	v_pk_fma_f32 v[30:31], v[162:163], v[110:111], v[220:221]
	v_pk_fma_f32 v[24:25], v[156:157], v[104:105], v[214:215]
	v_pk_fma_f32 v[32:33], v[164:165], v[112:113], v[222:223]
	v_pk_fma_f32 v[18:19], v[174:175], v[82:83], v[18:19]
	v_pk_fma_f32 v[26:27], v[142:143], v[90:91], v[26:27]
	v_pk_fma_f32 v[20:21], v[176:177], v[84:85], v[20:21]
	v_pk_fma_f32 v[28:29], v[144:145], v[92:93], v[28:29]
	v_pk_fma_f32 v[22:23], v[182:183], v[86:87], v[22:23]
	v_pk_fma_f32 v[30:31], v[146:147], v[94:95], v[30:31]
	v_pk_fma_f32 v[24:25], v[184:185], v[88:89], v[24:25]
	v_pk_fma_f32 v[32:33], v[148:149], v[96:97], v[32:33]
	v_pk_fma_f32 v[18:19], v[192:193], v[66:67], v[18:19]
	v_pk_fma_f32 v[26:27], v[200:201], v[74:75], v[26:27]
	v_pk_fma_f32 v[20:21], v[194:195], v[68:69], v[20:21]
	v_pk_fma_f32 v[28:29], v[202:203], v[76:77], v[28:29]
	v_pk_fma_f32 v[22:23], v[196:197], v[70:71], v[22:23]
	v_pk_fma_f32 v[30:31], v[204:205], v[78:79], v[30:31]
	v_pk_fma_f32 v[24:25], v[198:199], v[72:73], v[24:25]
	v_pk_fma_f32 v[32:33], v[206:207], v[80:81], v[32:33]
	v_pk_mul_f32 v[34:35], v[18:19], v[42:43] op_sel_hi:[1,0]
	v_pk_mul_f32 v[36:37], v[20:21], v[42:43] op_sel_hi:[1,0]
	v_pk_mul_f32 v[38:39], v[22:23], v[42:43] op_sel_hi:[1,0]
	v_pk_mul_f32 v[40:41], v[24:25], v[42:43] op_sel_hi:[1,0]
	v_exp_f32_e32 v34, v34
	v_exp_f32_e32 v35, v35
	v_exp_f32_e32 v36, v36
	v_exp_f32_e32 v37, v37
	v_exp_f32_e32 v38, v38
	v_exp_f32_e32 v39, v39
	v_exp_f32_e32 v40, v40
	v_exp_f32_e32 v41, v41
	v_pk_add_f32 v[34:35], v[34:35], 1.0 op_sel_hi:[1,0]
	v_pk_add_f32 v[36:37], v[36:37], 1.0 op_sel_hi:[1,0]
	v_pk_add_f32 v[38:39], v[38:39], 1.0 op_sel_hi:[1,0]
	v_pk_add_f32 v[40:41], v[40:41], 1.0 op_sel_hi:[1,0]
	v_rcp_f32_e32 v34, v34
	v_rcp_f32_e32 v35, v35
	v_rcp_f32_e32 v36, v36
	v_rcp_f32_e32 v37, v37
	v_rcp_f32_e32 v38, v38
	v_rcp_f32_e32 v39, v39
	v_rcp_f32_e32 v40, v40
	v_rcp_f32_e32 v41, v41
	v_pk_mul_f32 v[18:19], v[18:19], v[34:35]
	v_pk_mul_f32 v[20:21], v[20:21], v[36:37]
	v_pk_mul_f32 v[22:23], v[22:23], v[38:39]
	v_pk_mul_f32 v[24:25], v[24:25], v[40:41]
	v_pk_mul_f32 v[18:19], v[26:27], v[18:19]
	v_pk_mul_f32 v[20:21], v[28:29], v[20:21]
	v_pk_mul_f32 v[22:23], v[30:31], v[22:23]
	v_pk_mul_f32 v[24:25], v[32:33], v[24:25]
	v_cvt_pk_bf16_f32 v34, v18, v19
	v_cvt_pk_bf16_f32 v35, v20, v21
	v_cvt_pk_bf16_f32 v36, v22, v23
	v_cvt_pk_bf16_f32 v37, v24, v25
	global_store_dwordx4 v[50:51], v[34:37], off sc1
	s_and_b64 vcc, exec, s[78:79]
	s_cbranch_vccz .Luc_skip1
	v_mov_b64_e32 v[66:67], v[2:3]
	v_mov_b64_e32 v[68:69], v[4:5]
	v_mov_b64_e32 v[70:71], v[6:7]
	v_mov_b64_e32 v[72:73], v[8:9]
	v_mov_b64_e32 v[74:75], v[10:11]
	v_mov_b64_e32 v[76:77], v[12:13]
	v_mov_b64_e32 v[78:79], v[14:15]
	v_mov_b64_e32 v[80:81], v[16:17]

.Luc_fast2:
	v_pk_fma_f32 v[18:19], v[150:151], v[66:67], v[208:209]
	v_pk_fma_f32 v[26:27], v[158:159], v[74:75], v[216:217]
	v_pk_fma_f32 v[20:21], v[152:153], v[68:69], v[210:211]
	v_pk_fma_f32 v[28:29], v[160:161], v[76:77], v[218:219]
	v_pk_fma_f32 v[22:23], v[154:155], v[70:71], v[212:213]
	v_pk_fma_f32 v[30:31], v[162:163], v[78:79], v[220:221]
	v_pk_fma_f32 v[24:25], v[156:157], v[72:73], v[214:215]
	v_pk_fma_f32 v[32:33], v[164:165], v[80:81], v[222:223]
	v_pk_fma_f32 v[18:19], v[174:175], v[98:99], v[18:19]
	v_pk_fma_f32 v[26:27], v[142:143], v[106:107], v[26:27]
	v_pk_fma_f32 v[20:21], v[176:177], v[100:101], v[20:21]
	v_pk_fma_f32 v[28:29], v[144:145], v[108:109], v[28:29]
	v_pk_fma_f32 v[22:23], v[182:183], v[102:103], v[22:23]
	v_pk_fma_f32 v[30:31], v[146:147], v[110:111], v[30:31]
	v_pk_fma_f32 v[24:25], v[184:185], v[104:105], v[24:25]
	v_pk_fma_f32 v[32:33], v[148:149], v[112:113], v[32:33]
	v_pk_fma_f32 v[18:19], v[192:193], v[82:83], v[18:19]
	v_pk_fma_f32 v[26:27], v[200:201], v[90:91], v[26:27]
	v_pk_fma_f32 v[20:21], v[194:195], v[84:85], v[20:21]
	v_pk_fma_f32 v[28:29], v[202:203], v[92:93], v[28:29]
	v_pk_fma_f32 v[22:23], v[196:197], v[86:87], v[22:23]
	v_pk_fma_f32 v[30:31], v[204:205], v[94:95], v[30:31]
	v_pk_fma_f32 v[24:25], v[198:199], v[88:89], v[24:25]
	v_pk_fma_f32 v[32:33], v[206:207], v[96:97], v[32:33]
	v_pk_mul_f32 v[34:35], v[18:19], v[42:43] op_sel_hi:[1,0]
	v_pk_mul_f32 v[36:37], v[20:21], v[42:43] op_sel_hi:[1,0]
	v_pk_mul_f32 v[38:39], v[22:23], v[42:43] op_sel_hi:[1,0]
	v_pk_mul_f32 v[40:41], v[24:25], v[42:43] op_sel_hi:[1,0]
	v_exp_f32_e32 v34, v34
	v_exp_f32_e32 v35, v35
	v_exp_f32_e32 v36, v36
	v_exp_f32_e32 v37, v37
	v_exp_f32_e32 v38, v38
	v_exp_f32_e32 v39, v39
	v_exp_f32_e32 v40, v40
	v_exp_f32_e32 v41, v41
	v_pk_add_f32 v[34:35], v[34:35], 1.0 op_sel_hi:[1,0]
	v_pk_add_f32 v[36:37], v[36:37], 1.0 op_sel_hi:[1,0]
	v_pk_add_f32 v[38:39], v[38:39], 1.0 op_sel_hi:[1,0]
	v_pk_add_f32 v[40:41], v[40:41], 1.0 op_sel_hi:[1,0]
	v_rcp_f32_e32 v34, v34
	v_rcp_f32_e32 v35, v35
	v_rcp_f32_e32 v36, v36
	v_rcp_f32_e32 v37, v37
	v_rcp_f32_e32 v38, v38
	v_rcp_f32_e32 v39, v39
	v_rcp_f32_e32 v40, v40
	v_rcp_f32_e32 v41, v41
	v_pk_mul_f32 v[18:19], v[18:19], v[34:35]
	v_pk_mul_f32 v[20:21], v[20:21], v[36:37]
	v_pk_mul_f32 v[22:23], v[22:23], v[38:39]
	v_pk_mul_f32 v[24:25], v[24:25], v[40:41]
	v_pk_mul_f32 v[18:19], v[26:27], v[18:19]
	v_pk_mul_f32 v[20:21], v[28:29], v[20:21]
	v_pk_mul_f32 v[22:23], v[30:31], v[22:23]
	v_pk_mul_f32 v[24:25], v[32:33], v[24:25]
	v_cvt_pk_bf16_f32 v34, v18, v19
	v_cvt_pk_bf16_f32 v35, v20, v21
	v_cvt_pk_bf16_f32 v36, v22, v23
	v_cvt_pk_bf16_f32 v37, v24, v25
	global_store_dwordx4 v[50:51], v[34:37], off sc1
	s_and_b64 vcc, exec, s[78:79]
	s_cbranch_vccz .Luc_skip2
	v_mov_b64_e32 v[82:83], v[2:3]
	v_mov_b64_e32 v[84:85], v[4:5]
	v_mov_b64_e32 v[86:87], v[6:7]
	v_mov_b64_e32 v[88:89], v[8:9]
	v_mov_b64_e32 v[90:91], v[10:11]
	v_mov_b64_e32 v[92:93], v[12:13]
	v_mov_b64_e32 v[94:95], v[14:15]
	v_mov_b64_e32 v[96:97], v[16:17]
